# P6 epilogue v2: rs2 of the M-tile rows computed once per M-tile change into 1KiB extra static LDS and re-read per tile (no per-tile partial-sum loads/reduction)
# speedup vs baseline: 1.0289x; 1.0143x over previous
; template <class Epi>
; __device__ __forceinline__ void gemm_phase(const u16* A, const u16* Bt, int K, int nN, Epi epi) {
;   {
;     int x = epi.p.vx, j = epi.p.vj;
;     int li = j;
;     int mg = li / (nN * 8), rem = li % (nN * 8);
;     int brow = (x * 32 + mg * 8 + (rem & 7)) * 256, bcol = (rem >> 3) * 256;
;     for (int rd = 0; rd < nN; ++rd) {
;       int nbrow = 0, nbcol = 0;
;       bool has_next = rd + 1 < nN;
;       if (has_next) {
;         int l2 = (rd + 1) * 32 + j;
;         int mg2 = l2 / (nN * 8), rem2 = l2 % (nN * 8);
;         nbrow = (x * 32 + mg2 * 8 + (rem2 & 7)) * 256; nbcol = (rem2 >> 3) * 256;
;       }
;       gemm_tile(A, Bt, K, brow, bcol, rd == 0, has_next, nbrow, nbcol, epi);
;       brow = nbrow; bcol = nbcol;
;     }
;   __device__ __forceinline__ void operator()(f32x4 (&acc)[2][2][4][2], int brow, int bcol, int wr, int wc, int fr, int fq) const {
;     ...
;     float sv[2][4][4];
; #pragma unroll
;     for (int ai = 0; ai < 2; ++ai)
; #pragma unroll
;       for (int m = 0; m < 4; ++m)
; #pragma unroll
;         for (int j = 0; j < 4; ++j) sv[ai][m][j] = ssq1[(size_t)(brow + ai * 128 + wr * 64 + m * 16 + fq * 4 + j) * 16 + fr];
;     __builtin_amdgcn_sched_barrier(0);
; #pragma unroll
;     for (int ai = 0; ai < 2; ++ai)
; #pragma unroll
;       for (int m = 0; m < 4; ++m) {
;         int row0 = brow + ai * 128 + wr * 64 + m * 16 + fq * 4;
;         float rs[4];
; #pragma unroll
;         for (int j = 0; j < 4; ++j) rs[j] = rsqrtf(row16_sum(sv[ai][m][j]) * (1.f / 1024.f) + 1e-6f);
.LBB0_578:
	s_or_b64 exec, exec, s[0:1]
	s_add_u32 s25, s34, 0x1e200000
	s_mul_hi_i32 s0, s80, 0x2e8ba2e9
	s_addc_u32 s27, s35, 0
	s_lshr_b32 s1, s0, 31
	s_ashr_i32 s0, s0, 5
	s_add_i32 s0, s0, s1
	s_mul_i32 s1, s0, 0xb0
	s_sub_i32 s1, s80, s1
	s_lshl_b32 s0, s0, 3
	s_add_i32 s0, s0, s81
	s_and_b32 s2, s1, 7
	s_or_b32 s0, s0, s2
	s_lshl_b32 s2, s0, 8
	s_lshl_b32 s0, s1, 5
	s_and_b32 s0, s0, 0xffffff00
	s_mov_b32 s1, 0
	v_mov_b32_e32 v129, 0
	s_mov_b64 s[10:11], 0x80
	s_movk_i32 s60, 0x3c0
	s_mov_b64 s[12:13], 0x16000080
	s_mov_b64 s[14:15], 0x1e200100
	s_mov_b64 s[16:17], 0x16000100
	s_mov_b64 s[18:19], 0x1e200180
	s_mov_b64 s[20:21], 0x16000180
	s_mov_b64 s[22:23], 0x780
	s_movk_i32 s61, 0x100
	s_mov_b32 s24, 0x3a800000
	s_mov_b32 s26, 0x358637bd
	s_mov_b32 s62, 0x800000
	s_movk_i32 s63, 0x1600
	v_mov_b32_e32 v162, 1
	s_mov_b32 s101, -1
	s_waitcnt lgkmcnt(0)
	s_barrier
	s_branch .LBB0_580
.LBB0_579:
	v_mbcnt_lo_u32_b32 v163, -1, 0
	v_mbcnt_hi_u32_b32 v163, -1, v163
	v_mov_b32_e32 v165, 0x358637bd
	s_cmp_eq_u32 s101, s2
	s_cbranch_scc1 .Lmy_gu_have_rs
	s_mov_b32 s101, s2
	s_cmpk_lt_u32 s33, 0x100
	s_cbranch_scc0 .Lmy_gu_rs_sync
	s_lshl_b32 s3, s2, 6
	s_add_u32 s98, s8, s3
	s_addc_u32 s99, s9, 0
	v_add_u32_e32 v172, s33, v163
	v_lshlrev_b32_e32 v173, 6, v172
	global_load_dwordx4 v[130:133], v173, s[98:99]
	global_load_dwordx4 v[134:137], v173, s[98:99] offset:16
	global_load_dwordx4 v[138:141], v173, s[98:99] offset:32
	global_load_dwordx4 v[142:145], v173, s[98:99] offset:48
	v_lshlrev_b32_e32 v172, 2, v172
	v_add_u32_e32 v172, 0x20010, v172
	s_waitcnt vmcnt(0)
	v_add_f32_e32 v130, v130, v138
	v_add_f32_e32 v131, v131, v139
	v_add_f32_e32 v132, v132, v140
	v_add_f32_e32 v133, v133, v141
	v_add_f32_e32 v134, v134, v142
	v_add_f32_e32 v135, v135, v143
	v_add_f32_e32 v136, v136, v144
	v_add_f32_e32 v137, v137, v145
	v_add_f32_e32 v130, v130, v134
	v_add_f32_e32 v131, v131, v135
	v_add_f32_e32 v132, v132, v136
	v_add_f32_e32 v133, v133, v137
	v_add_f32_e32 v130, v130, v132
	v_add_f32_e32 v131, v131, v133
	v_add_f32_e32 v130, v130, v131
	v_fma_f32 v130, v130, s24, v165
	v_rsq_f32_e32 v130, v130
	s_nop 0
	ds_write_b32 v172, v130
.Lmy_gu_rs_sync:
	s_waitcnt lgkmcnt(0)
	s_barrier
.Lmy_gu_have_rs:
	s_lshr_b32 s3, s33, 8
	v_lshrrev_b32_e32 v167, 4, v163
	v_and_b32_e32 v168, 1, v163
	s_lshl_b32 s4, s3, 8
	s_add_i32 s4, s4, 0x20010
	v_lshl_add_u32 v171, v167, 4, s4
	ds_read_b128 v[130:133], v171
	ds_read_b128 v[134:137], v171 offset:64
	ds_read_b128 v[138:141], v171 offset:128
	ds_read_b128 v[142:145], v171 offset:192
	ds_read_b128 v[146:149], v171 offset:512
	ds_read_b128 v[150:153], v171 offset:576
	ds_read_b128 v[154:157], v171 offset:640
	ds_read_b128 v[158:161], v171 offset:704
	s_ashr_i32 s0, s0, 1
	s_and_b32 s0, s0, 0xffffff80
	s_bfe_u32 s4, s33, 0x20006
	s_lshl_b32 s4, s4, 5
	s_add_i32 s0, s0, s4
	s_lshl_b32 s3, s3, 6
	s_add_i32 s3, s3, s2
	v_lshl_add_u32 v166, v167, 2, v168
	v_add_u32_e32 v166, s3, v166
	v_mul_u32_u24_e32 v166, 0x1600, v166
	v_and_b32_e32 v172, 14, v163
	v_add_u32_e32 v172, s0, v172
	v_lshl_add_u32 v166, v172, 1, v166
	v_mov_b32_e32 v164, 0x05040100
	v_mov_b32_e32 v173, 0x03020706
	v_cmp_eq_u32_e32 vcc, 1, v168
	s_nop 1
	v_cndmask_b32_e32 v164, v164, v173, vcc
	s_waitcnt lgkmcnt(0)
	v_mov_b32_e32 v169, v166
	v_add_u32_e32 v170, 0x2c00, v166
	v_mul_f32_e32 v120, v120, v130
	v_mul_f32_e32 v121, v121, v131
	v_mul_f32_e32 v122, v122, v132
	v_mul_f32_e32 v123, v123, v133
	v_mul_f32_e32 v112, v112, v130
	v_mul_f32_e32 v113, v113, v131
	v_mul_f32_e32 v114, v114, v132
	v_mul_f32_e32 v115, v115, v133
	v_mul_f32_e32 v124, v124, v130
	v_mul_f32_e32 v125, v125, v131
	v_mul_f32_e32 v126, v126, v132
	v_mul_f32_e32 v127, v127, v133
	v_mul_f32_e32 v116, v116, v130
	v_mul_f32_e32 v117, v117, v131
	v_mul_f32_e32 v118, v118, v132
	v_mul_f32_e32 v119, v119, v133
	v_mul_f32_e32 v172, 0xbfb8aa3b, v120
	v_mul_f32_e32 v173, 0xbfb8aa3b, v121
	v_mul_f32_e32 v174, 0xbfb8aa3b, v122
	v_mul_f32_e32 v175, 0xbfb8aa3b, v123
	v_mul_f32_e32 v176, 0xbfb8aa3b, v112
	v_mul_f32_e32 v177, 0xbfb8aa3b, v113
	v_mul_f32_e32 v178, 0xbfb8aa3b, v114
	v_mul_f32_e32 v179, 0xbfb8aa3b, v115
	v_exp_f32_e32 v172, v172
	v_exp_f32_e32 v173, v173
	v_exp_f32_e32 v174, v174
	v_exp_f32_e32 v175, v175
	v_exp_f32_e32 v176, v176
	v_exp_f32_e32 v177, v177
	v_exp_f32_e32 v178, v178
	v_exp_f32_e32 v179, v179
	v_add_f32_e32 v172, 1.0, v172
	v_add_f32_e32 v173, 1.0, v173
	v_add_f32_e32 v174, 1.0, v174
	v_add_f32_e32 v175, 1.0, v175
	v_add_f32_e32 v176, 1.0, v176
	v_add_f32_e32 v177, 1.0, v177
	v_add_f32_e32 v178, 1.0, v178
	v_add_f32_e32 v179, 1.0, v179
	v_rcp_f32_e32 v172, v172
	v_rcp_f32_e32 v173, v173
	v_rcp_f32_e32 v174, v174
	v_rcp_f32_e32 v175, v175
	v_rcp_f32_e32 v176, v176
	v_rcp_f32_e32 v177, v177
	v_rcp_f32_e32 v178, v178
	v_rcp_f32_e32 v179, v179
	v_mul_f32_e32 v172, v120, v172
	v_mul_f32_e32 v173, v121, v173
	v_mul_f32_e32 v174, v122, v174
	v_mul_f32_e32 v175, v123, v175
	v_mul_f32_e32 v176, v112, v176
	v_mul_f32_e32 v177, v113, v177
	v_mul_f32_e32 v178, v114, v178
	v_mul_f32_e32 v179, v115, v179
	v_mul_f32_e32 v120, v124, v172
	v_mul_f32_e32 v121, v125, v173
	v_mul_f32_e32 v122, v126, v174
	v_mul_f32_e32 v123, v127, v175
	v_mul_f32_e32 v112, v116, v176
	v_mul_f32_e32 v113, v117, v177
	v_mul_f32_e32 v114, v118, v178
	v_mul_f32_e32 v115, v119, v179
	v_cvt_pk_bf16_f32 v180, v120, v121
	v_cvt_pk_bf16_f32 v181, v122, v123
	v_cvt_pk_bf16_f32 v182, v112, v113
	v_cvt_pk_bf16_f32 v183, v114, v115
	v_mov_b32_dpp v184, v180 quad_perm:[1,0,3,2] row_mask:0xf bank_mask:0xf bound_ctrl:1
	v_mov_b32_dpp v185, v181 quad_perm:[1,0,3,2] row_mask:0xf bank_mask:0xf bound_ctrl:1
; __device__ __forceinline__ float fast_silu(float z) { return z * __builtin_amdgcn_rcpf(1.f + __expf(-z)); }
; __device__ __forceinline__ void store_rm4(u16* dst, size_t ld, int row0, int c, float v0, float v1, float v2, float v3, bool odd) {
;   {
;     float s = odd ? v0 : v1, r = dpp_swap1(s);
;     float lo = odd ? r : v0, hi = odd ? v1 : r;
;     *(unsigned*)(dst + (size_t)(row0 + (odd ? 1 : 0)) * ld + (c - (odd ? 1 : 0))) = pack2(lo, hi);
;   }
;   {
;     float s = odd ? v2 : v3, r = dpp_swap1(s);
;     float lo = odd ? r : v2, hi = odd ? v3 : r;
;     *(unsigned*)(dst + (size_t)(row0 + 2 + (odd ? 1 : 0)) * ld + (c - (odd ? 1 : 0))) = pack2(lo, hi);
;   }
; }
;   __device__ __forceinline__ void operator()(f32x4 (&acc)[2][2][4][2], int brow, int bcol, int wr, int wc, int fr, int fq) const {
;     ...
; #pragma unroll
;         for (int n = 0; n < 2; ++n) {
;           float a[4];
; #pragma unroll
;           for (int j = 0; j < 4; ++j) {
;             float g = acc[ai][0][m][n][j] * rs[j], u = acc[ai][1][m][n][j] * rs[j];
;             a[j] = fast_silu(g) * u;
;           }
;           store_rm4(act, 2816, row0, t * 128 + wc * 32 + n * 16 + fr, a[0], a[1], a[2], a[3], fr & 1);
;         }
	v_mov_b32_dpp v186, v182 quad_perm:[1,0,3,2] row_mask:0xf bank_mask:0xf bound_ctrl:1
	v_mov_b32_dpp v187, v183 quad_perm:[1,0,3,2] row_mask:0xf bank_mask:0xf bound_ctrl:1
	v_perm_b32 v180, v184, v180, v164
	v_perm_b32 v181, v185, v181, v164
	v_perm_b32 v182, v186, v182, v164
	v_perm_b32 v183, v187, v183, v164
	global_store_dword v169, v180, s[34:35]
	global_store_dword v170, v181, s[34:35]
	global_store_dword v169, v182, s[34:35] offset:32
	global_store_dword v170, v183, s[34:35] offset:32
	v_add_u32_e32 v169, 0x16000, v166
	v_add_u32_e32 v170, 0x18c00, v166
	v_mul_f32_e32 v104, v104, v134
	v_mul_f32_e32 v105, v105, v135
	v_mul_f32_e32 v106, v106, v136
	v_mul_f32_e32 v107, v107, v137
	v_mul_f32_e32 v96, v96, v134
	v_mul_f32_e32 v97, v97, v135
	v_mul_f32_e32 v98, v98, v136
	v_mul_f32_e32 v99, v99, v137
	v_mul_f32_e32 v108, v108, v134
	v_mul_f32_e32 v109, v109, v135
	v_mul_f32_e32 v110, v110, v136
	v_mul_f32_e32 v111, v111, v137
	v_mul_f32_e32 v100, v100, v134
	v_mul_f32_e32 v101, v101, v135
	v_mul_f32_e32 v102, v102, v136
	v_mul_f32_e32 v103, v103, v137
	v_mul_f32_e32 v172, 0xbfb8aa3b, v104
	v_mul_f32_e32 v173, 0xbfb8aa3b, v105
	v_mul_f32_e32 v174, 0xbfb8aa3b, v106
	v_mul_f32_e32 v175, 0xbfb8aa3b, v107
	v_mul_f32_e32 v176, 0xbfb8aa3b, v96
	v_mul_f32_e32 v177, 0xbfb8aa3b, v97
	v_mul_f32_e32 v178, 0xbfb8aa3b, v98
	v_mul_f32_e32 v179, 0xbfb8aa3b, v99
	v_exp_f32_e32 v172, v172
	v_exp_f32_e32 v173, v173
	v_exp_f32_e32 v174, v174
	v_exp_f32_e32 v175, v175
	v_exp_f32_e32 v176, v176
	v_exp_f32_e32 v177, v177
	v_exp_f32_e32 v178, v178
	v_exp_f32_e32 v179, v179
	v_add_f32_e32 v172, 1.0, v172
	v_add_f32_e32 v173, 1.0, v173
	v_add_f32_e32 v174, 1.0, v174
	v_add_f32_e32 v175, 1.0, v175
	v_add_f32_e32 v176, 1.0, v176
	v_add_f32_e32 v177, 1.0, v177
	v_add_f32_e32 v178, 1.0, v178
	v_add_f32_e32 v179, 1.0, v179
	v_rcp_f32_e32 v172, v172
	v_rcp_f32_e32 v173, v173
	v_rcp_f32_e32 v174, v174
	v_rcp_f32_e32 v175, v175
	v_rcp_f32_e32 v176, v176
	v_rcp_f32_e32 v177, v177
	v_rcp_f32_e32 v178, v178
	v_rcp_f32_e32 v179, v179
	v_mul_f32_e32 v172, v104, v172
	v_mul_f32_e32 v173, v105, v173
	v_mul_f32_e32 v174, v106, v174
	v_mul_f32_e32 v175, v107, v175
	v_mul_f32_e32 v176, v96, v176
	v_mul_f32_e32 v177, v97, v177
	v_mul_f32_e32 v178, v98, v178
	v_mul_f32_e32 v179, v99, v179
	v_mul_f32_e32 v104, v108, v172
	v_mul_f32_e32 v105, v109, v173
	v_mul_f32_e32 v106, v110, v174
	v_mul_f32_e32 v107, v111, v175
	v_mul_f32_e32 v96, v100, v176
	v_mul_f32_e32 v97, v101, v177
	v_mul_f32_e32 v98, v102, v178
	v_mul_f32_e32 v99, v103, v179
	v_cvt_pk_bf16_f32 v180, v104, v105
	v_cvt_pk_bf16_f32 v181, v106, v107
	v_cvt_pk_bf16_f32 v182, v96, v97
	v_cvt_pk_bf16_f32 v183, v98, v99
	v_mov_b32_dpp v184, v180 quad_perm:[1,0,3,2] row_mask:0xf bank_mask:0xf bound_ctrl:1
	v_mov_b32_dpp v185, v181 quad_perm:[1,0,3,2] row_mask:0xf bank_mask:0xf bound_ctrl:1
	v_mov_b32_dpp v186, v182 quad_perm:[1,0,3,2] row_mask:0xf bank_mask:0xf bound_ctrl:1
	v_mov_b32_dpp v187, v183 quad_perm:[1,0,3,2] row_mask:0xf bank_mask:0xf bound_ctrl:1
	v_perm_b32 v180, v184, v180, v164
	v_perm_b32 v181, v185, v181, v164
	v_perm_b32 v182, v186, v182, v164
	v_perm_b32 v183, v187, v183, v164
	global_store_dword v169, v180, s[34:35]
	global_store_dword v170, v181, s[34:35]
	global_store_dword v169, v182, s[34:35] offset:32
	global_store_dword v170, v183, s[34:35] offset:32
	v_add_u32_e32 v169, 0x2c000, v166
	v_add_u32_e32 v170, 0x2ec00, v166
	v_mul_f32_e32 v88, v88, v138
	v_mul_f32_e32 v89, v89, v139
	v_mul_f32_e32 v90, v90, v140
	v_mul_f32_e32 v91, v91, v141
	v_mul_f32_e32 v80, v80, v138
	v_mul_f32_e32 v81, v81, v139
	v_mul_f32_e32 v82, v82, v140
	v_mul_f32_e32 v83, v83, v141
	v_mul_f32_e32 v92, v92, v138
	v_mul_f32_e32 v93, v93, v139
	v_mul_f32_e32 v94, v94, v140
	v_mul_f32_e32 v95, v95, v141
	v_mul_f32_e32 v84, v84, v138
	v_mul_f32_e32 v85, v85, v139
	v_mul_f32_e32 v86, v86, v140
	v_mul_f32_e32 v87, v87, v141
	v_mul_f32_e32 v172, 0xbfb8aa3b, v88
	v_mul_f32_e32 v173, 0xbfb8aa3b, v89
	v_mul_f32_e32 v174, 0xbfb8aa3b, v90
	v_mul_f32_e32 v175, 0xbfb8aa3b, v91
	v_mul_f32_e32 v176, 0xbfb8aa3b, v80
	v_mul_f32_e32 v177, 0xbfb8aa3b, v81
	v_mul_f32_e32 v178, 0xbfb8aa3b, v82
	v_mul_f32_e32 v179, 0xbfb8aa3b, v83
	v_exp_f32_e32 v172, v172
	v_exp_f32_e32 v173, v173
	v_exp_f32_e32 v174, v174
	v_exp_f32_e32 v175, v175
	v_exp_f32_e32 v176, v176
	v_exp_f32_e32 v177, v177
	v_exp_f32_e32 v178, v178
	v_exp_f32_e32 v179, v179
	v_add_f32_e32 v172, 1.0, v172
	v_add_f32_e32 v173, 1.0, v173
	v_add_f32_e32 v174, 1.0, v174
	v_add_f32_e32 v175, 1.0, v175
	v_add_f32_e32 v176, 1.0, v176
	v_add_f32_e32 v177, 1.0, v177
	v_add_f32_e32 v178, 1.0, v178
	v_add_f32_e32 v179, 1.0, v179
	v_rcp_f32_e32 v172, v172
	v_rcp_f32_e32 v173, v173
	v_rcp_f32_e32 v174, v174
	v_rcp_f32_e32 v175, v175
	v_rcp_f32_e32 v176, v176
	v_rcp_f32_e32 v177, v177
	v_rcp_f32_e32 v178, v178
	v_rcp_f32_e32 v179, v179
	v_mul_f32_e32 v172, v88, v172
	v_mul_f32_e32 v173, v89, v173
	v_mul_f32_e32 v174, v90, v174
	v_mul_f32_e32 v175, v91, v175
	v_mul_f32_e32 v176, v80, v176
	v_mul_f32_e32 v177, v81, v177
	v_mul_f32_e32 v178, v82, v178
	v_mul_f32_e32 v179, v83, v179
	v_mul_f32_e32 v88, v92, v172
	v_mul_f32_e32 v89, v93, v173
	v_mul_f32_e32 v90, v94, v174
	v_mul_f32_e32 v91, v95, v175
	v_mul_f32_e32 v80, v84, v176
	v_mul_f32_e32 v81, v85, v177
	v_mul_f32_e32 v82, v86, v178
	v_mul_f32_e32 v83, v87, v179
	v_cvt_pk_bf16_f32 v180, v88, v89
	v_cvt_pk_bf16_f32 v181, v90, v91
	v_cvt_pk_bf16_f32 v182, v80, v81
	v_cvt_pk_bf16_f32 v183, v82, v83
	v_mov_b32_dpp v184, v180 quad_perm:[1,0,3,2] row_mask:0xf bank_mask:0xf bound_ctrl:1
	v_mov_b32_dpp v185, v181 quad_perm:[1,0,3,2] row_mask:0xf bank_mask:0xf bound_ctrl:1
; __device__ __forceinline__ float fast_silu(float z) { return z * __builtin_amdgcn_rcpf(1.f + __expf(-z)); }
; __device__ __forceinline__ void store_rm4(u16* dst, size_t ld, int row0, int c, float v0, float v1, float v2, float v3, bool odd) {
;   {
;     float s = odd ? v0 : v1, r = dpp_swap1(s);
;     float lo = odd ? r : v0, hi = odd ? v1 : r;
;     *(unsigned*)(dst + (size_t)(row0 + (odd ? 1 : 0)) * ld + (c - (odd ? 1 : 0))) = pack2(lo, hi);
;   }
;   {
;     float s = odd ? v2 : v3, r = dpp_swap1(s);
;     float lo = odd ? r : v2, hi = odd ? v3 : r;
;     *(unsigned*)(dst + (size_t)(row0 + 2 + (odd ? 1 : 0)) * ld + (c - (odd ? 1 : 0))) = pack2(lo, hi);
;   }
; }
;   __device__ __forceinline__ void operator()(f32x4 (&acc)[2][2][4][2], int brow, int bcol, int wr, int wc, int fr, int fq) const {
;     ...
; #pragma unroll
;         for (int n = 0; n < 2; ++n) {
;           float a[4];
; #pragma unroll
;           for (int j = 0; j < 4; ++j) {
;             float g = acc[ai][0][m][n][j] * rs[j], u = acc[ai][1][m][n][j] * rs[j];
;             a[j] = fast_silu(g) * u;
;           }
;           store_rm4(act, 2816, row0, t * 128 + wc * 32 + n * 16 + fr, a[0], a[1], a[2], a[3], fr & 1);
;         }
	v_mov_b32_dpp v186, v182 quad_perm:[1,0,3,2] row_mask:0xf bank_mask:0xf bound_ctrl:1
	v_mov_b32_dpp v187, v183 quad_perm:[1,0,3,2] row_mask:0xf bank_mask:0xf bound_ctrl:1
	v_perm_b32 v180, v184, v180, v164
	v_perm_b32 v181, v185, v181, v164
	v_perm_b32 v182, v186, v182, v164
	v_perm_b32 v183, v187, v183, v164
	global_store_dword v169, v180, s[34:35]
	global_store_dword v170, v181, s[34:35]
	global_store_dword v169, v182, s[34:35] offset:32
	global_store_dword v170, v183, s[34:35] offset:32
	v_add_u32_e32 v169, 0x42000, v166
	v_add_u32_e32 v170, 0x44c00, v166
	v_mul_f32_e32 v72, v72, v142
	v_mul_f32_e32 v73, v73, v143
	v_mul_f32_e32 v74, v74, v144
	v_mul_f32_e32 v75, v75, v145
	v_mul_f32_e32 v64, v64, v142
	v_mul_f32_e32 v65, v65, v143
	v_mul_f32_e32 v66, v66, v144
	v_mul_f32_e32 v67, v67, v145
	v_mul_f32_e32 v76, v76, v142
	v_mul_f32_e32 v77, v77, v143
	v_mul_f32_e32 v78, v78, v144
	v_mul_f32_e32 v79, v79, v145
	v_mul_f32_e32 v68, v68, v142
	v_mul_f32_e32 v69, v69, v143
	v_mul_f32_e32 v70, v70, v144
	v_mul_f32_e32 v71, v71, v145
	v_mul_f32_e32 v172, 0xbfb8aa3b, v72
	v_mul_f32_e32 v173, 0xbfb8aa3b, v73
	v_mul_f32_e32 v174, 0xbfb8aa3b, v74
	v_mul_f32_e32 v175, 0xbfb8aa3b, v75
	v_mul_f32_e32 v176, 0xbfb8aa3b, v64
	v_mul_f32_e32 v177, 0xbfb8aa3b, v65
	v_mul_f32_e32 v178, 0xbfb8aa3b, v66
	v_mul_f32_e32 v179, 0xbfb8aa3b, v67
	v_exp_f32_e32 v172, v172
	v_exp_f32_e32 v173, v173
	v_exp_f32_e32 v174, v174
	v_exp_f32_e32 v175, v175
	v_exp_f32_e32 v176, v176
	v_exp_f32_e32 v177, v177
	v_exp_f32_e32 v178, v178
	v_exp_f32_e32 v179, v179
	v_add_f32_e32 v172, 1.0, v172
	v_add_f32_e32 v173, 1.0, v173
	v_add_f32_e32 v174, 1.0, v174
	v_add_f32_e32 v175, 1.0, v175
	v_add_f32_e32 v176, 1.0, v176
	v_add_f32_e32 v177, 1.0, v177
	v_add_f32_e32 v178, 1.0, v178
	v_add_f32_e32 v179, 1.0, v179
	v_rcp_f32_e32 v172, v172
	v_rcp_f32_e32 v173, v173
	v_rcp_f32_e32 v174, v174
	v_rcp_f32_e32 v175, v175
	v_rcp_f32_e32 v176, v176
	v_rcp_f32_e32 v177, v177
	v_rcp_f32_e32 v178, v178
	v_rcp_f32_e32 v179, v179
	v_mul_f32_e32 v172, v72, v172
	v_mul_f32_e32 v173, v73, v173
	v_mul_f32_e32 v174, v74, v174
	v_mul_f32_e32 v175, v75, v175
	v_mul_f32_e32 v176, v64, v176
	v_mul_f32_e32 v177, v65, v177
	v_mul_f32_e32 v178, v66, v178
	v_mul_f32_e32 v179, v67, v179
	v_mul_f32_e32 v72, v76, v172
	v_mul_f32_e32 v73, v77, v173
	v_mul_f32_e32 v74, v78, v174
	v_mul_f32_e32 v75, v79, v175
	v_mul_f32_e32 v64, v68, v176
	v_mul_f32_e32 v65, v69, v177
	v_mul_f32_e32 v66, v70, v178
	v_mul_f32_e32 v67, v71, v179
	v_cvt_pk_bf16_f32 v180, v72, v73
	v_cvt_pk_bf16_f32 v181, v74, v75
	v_cvt_pk_bf16_f32 v182, v64, v65
	v_cvt_pk_bf16_f32 v183, v66, v67
	v_mov_b32_dpp v184, v180 quad_perm:[1,0,3,2] row_mask:0xf bank_mask:0xf bound_ctrl:1
	v_mov_b32_dpp v185, v181 quad_perm:[1,0,3,2] row_mask:0xf bank_mask:0xf bound_ctrl:1
	v_mov_b32_dpp v186, v182 quad_perm:[1,0,3,2] row_mask:0xf bank_mask:0xf bound_ctrl:1
	v_mov_b32_dpp v187, v183 quad_perm:[1,0,3,2] row_mask:0xf bank_mask:0xf bound_ctrl:1
	v_perm_b32 v180, v184, v180, v164
	v_perm_b32 v181, v185, v181, v164
	v_perm_b32 v182, v186, v182, v164
	v_perm_b32 v183, v187, v183, v164
	global_store_dword v169, v180, s[34:35]
	global_store_dword v170, v181, s[34:35]
	global_store_dword v169, v182, s[34:35] offset:32
	global_store_dword v170, v183, s[34:35] offset:32
	v_add_u32_e32 v169, 0xb0000, v166
	v_add_u32_e32 v170, 0xb2c00, v166
	v_mul_f32_e32 v56, v56, v146
	v_mul_f32_e32 v57, v57, v147
	v_mul_f32_e32 v58, v58, v148
	v_mul_f32_e32 v59, v59, v149
	v_mul_f32_e32 v48, v48, v146
	v_mul_f32_e32 v49, v49, v147
	v_mul_f32_e32 v50, v50, v148
	v_mul_f32_e32 v51, v51, v149
	v_mul_f32_e32 v60, v60, v146
	v_mul_f32_e32 v61, v61, v147
	v_mul_f32_e32 v62, v62, v148
	v_mul_f32_e32 v63, v63, v149
	v_mul_f32_e32 v52, v52, v146
	v_mul_f32_e32 v53, v53, v147
	v_mul_f32_e32 v54, v54, v148
	v_mul_f32_e32 v55, v55, v149
	v_mul_f32_e32 v172, 0xbfb8aa3b, v56
	v_mul_f32_e32 v173, 0xbfb8aa3b, v57
	v_mul_f32_e32 v174, 0xbfb8aa3b, v58
	v_mul_f32_e32 v175, 0xbfb8aa3b, v59
	v_mul_f32_e32 v176, 0xbfb8aa3b, v48
	v_mul_f32_e32 v177, 0xbfb8aa3b, v49
	v_mul_f32_e32 v178, 0xbfb8aa3b, v50
	v_mul_f32_e32 v179, 0xbfb8aa3b, v51
	v_exp_f32_e32 v172, v172
	v_exp_f32_e32 v173, v173
	v_exp_f32_e32 v174, v174
	v_exp_f32_e32 v175, v175
	v_exp_f32_e32 v176, v176
	v_exp_f32_e32 v177, v177
	v_exp_f32_e32 v178, v178
	v_exp_f32_e32 v179, v179
	v_add_f32_e32 v172, 1.0, v172
	v_add_f32_e32 v173, 1.0, v173
	v_add_f32_e32 v174, 1.0, v174
	v_add_f32_e32 v175, 1.0, v175
	v_add_f32_e32 v176, 1.0, v176
	v_add_f32_e32 v177, 1.0, v177
	v_add_f32_e32 v178, 1.0, v178
	v_add_f32_e32 v179, 1.0, v179
	v_rcp_f32_e32 v172, v172
	v_rcp_f32_e32 v173, v173
	v_rcp_f32_e32 v174, v174
	v_rcp_f32_e32 v175, v175
	v_rcp_f32_e32 v176, v176
	v_rcp_f32_e32 v177, v177
	v_rcp_f32_e32 v178, v178
	v_rcp_f32_e32 v179, v179
	v_mul_f32_e32 v172, v56, v172
	v_mul_f32_e32 v173, v57, v173
	v_mul_f32_e32 v174, v58, v174
	v_mul_f32_e32 v175, v59, v175
	v_mul_f32_e32 v176, v48, v176
	v_mul_f32_e32 v177, v49, v177
	v_mul_f32_e32 v178, v50, v178
	v_mul_f32_e32 v179, v51, v179
	v_mul_f32_e32 v56, v60, v172
	v_mul_f32_e32 v57, v61, v173
	v_mul_f32_e32 v58, v62, v174
	v_mul_f32_e32 v59, v63, v175
	v_mul_f32_e32 v48, v52, v176
	v_mul_f32_e32 v49, v53, v177
	v_mul_f32_e32 v50, v54, v178
	v_mul_f32_e32 v51, v55, v179
	v_cvt_pk_bf16_f32 v180, v56, v57
	v_cvt_pk_bf16_f32 v181, v58, v59
	v_cvt_pk_bf16_f32 v182, v48, v49
	v_cvt_pk_bf16_f32 v183, v50, v51
	v_mov_b32_dpp v184, v180 quad_perm:[1,0,3,2] row_mask:0xf bank_mask:0xf bound_ctrl:1
	v_mov_b32_dpp v185, v181 quad_perm:[1,0,3,2] row_mask:0xf bank_mask:0xf bound_ctrl:1
; __device__ __forceinline__ float fast_silu(float z) { return z * __builtin_amdgcn_rcpf(1.f + __expf(-z)); }
; __device__ __forceinline__ void store_rm4(u16* dst, size_t ld, int row0, int c, float v0, float v1, float v2, float v3, bool odd) {
;   {
;     float s = odd ? v0 : v1, r = dpp_swap1(s);
;     float lo = odd ? r : v0, hi = odd ? v1 : r;
;     *(unsigned*)(dst + (size_t)(row0 + (odd ? 1 : 0)) * ld + (c - (odd ? 1 : 0))) = pack2(lo, hi);
;   }
;   {
;     float s = odd ? v2 : v3, r = dpp_swap1(s);
;     float lo = odd ? r : v2, hi = odd ? v3 : r;
;     *(unsigned*)(dst + (size_t)(row0 + 2 + (odd ? 1 : 0)) * ld + (c - (odd ? 1 : 0))) = pack2(lo, hi);
;   }
; }
;   __device__ __forceinline__ void operator()(f32x4 (&acc)[2][2][4][2], int brow, int bcol, int wr, int wc, int fr, int fq) const {
;     ...
; #pragma unroll
;         for (int n = 0; n < 2; ++n) {
;           float a[4];
; #pragma unroll
;           for (int j = 0; j < 4; ++j) {
;             float g = acc[ai][0][m][n][j] * rs[j], u = acc[ai][1][m][n][j] * rs[j];
;             a[j] = fast_silu(g) * u;
;           }
;           store_rm4(act, 2816, row0, t * 128 + wc * 32 + n * 16 + fr, a[0], a[1], a[2], a[3], fr & 1);
;         }
	v_mov_b32_dpp v186, v182 quad_perm:[1,0,3,2] row_mask:0xf bank_mask:0xf bound_ctrl:1
	v_mov_b32_dpp v187, v183 quad_perm:[1,0,3,2] row_mask:0xf bank_mask:0xf bound_ctrl:1
	v_perm_b32 v180, v184, v180, v164
	v_perm_b32 v181, v185, v181, v164
	v_perm_b32 v182, v186, v182, v164
	v_perm_b32 v183, v187, v183, v164
	global_store_dword v169, v180, s[34:35]
	global_store_dword v170, v181, s[34:35]
	global_store_dword v169, v182, s[34:35] offset:32
	global_store_dword v170, v183, s[34:35] offset:32
	v_add_u32_e32 v169, 0xc6000, v166
	v_add_u32_e32 v170, 0xc8c00, v166
	v_mul_f32_e32 v40, v40, v150
	v_mul_f32_e32 v41, v41, v151
	v_mul_f32_e32 v42, v42, v152
	v_mul_f32_e32 v43, v43, v153
	v_mul_f32_e32 v32, v32, v150
	v_mul_f32_e32 v33, v33, v151
	v_mul_f32_e32 v34, v34, v152
	v_mul_f32_e32 v35, v35, v153
	v_mul_f32_e32 v44, v44, v150
	v_mul_f32_e32 v45, v45, v151
	v_mul_f32_e32 v46, v46, v152
	v_mul_f32_e32 v47, v47, v153
	v_mul_f32_e32 v36, v36, v150
	v_mul_f32_e32 v37, v37, v151
	v_mul_f32_e32 v38, v38, v152
	v_mul_f32_e32 v39, v39, v153
	v_mul_f32_e32 v172, 0xbfb8aa3b, v40
	v_mul_f32_e32 v173, 0xbfb8aa3b, v41
	v_mul_f32_e32 v174, 0xbfb8aa3b, v42
	v_mul_f32_e32 v175, 0xbfb8aa3b, v43
	v_mul_f32_e32 v176, 0xbfb8aa3b, v32
	v_mul_f32_e32 v177, 0xbfb8aa3b, v33
	v_mul_f32_e32 v178, 0xbfb8aa3b, v34
	v_mul_f32_e32 v179, 0xbfb8aa3b, v35
	v_exp_f32_e32 v172, v172
	v_exp_f32_e32 v173, v173
	v_exp_f32_e32 v174, v174
	v_exp_f32_e32 v175, v175
	v_exp_f32_e32 v176, v176
	v_exp_f32_e32 v177, v177
	v_exp_f32_e32 v178, v178
	v_exp_f32_e32 v179, v179
	v_add_f32_e32 v172, 1.0, v172
	v_add_f32_e32 v173, 1.0, v173
	v_add_f32_e32 v174, 1.0, v174
	v_add_f32_e32 v175, 1.0, v175
	v_add_f32_e32 v176, 1.0, v176
	v_add_f32_e32 v177, 1.0, v177
	v_add_f32_e32 v178, 1.0, v178
	v_add_f32_e32 v179, 1.0, v179
	v_rcp_f32_e32 v172, v172
	v_rcp_f32_e32 v173, v173
	v_rcp_f32_e32 v174, v174
	v_rcp_f32_e32 v175, v175
	v_rcp_f32_e32 v176, v176
	v_rcp_f32_e32 v177, v177
	v_rcp_f32_e32 v178, v178
	v_rcp_f32_e32 v179, v179
	v_mul_f32_e32 v172, v40, v172
	v_mul_f32_e32 v173, v41, v173
	v_mul_f32_e32 v174, v42, v174
	v_mul_f32_e32 v175, v43, v175
	v_mul_f32_e32 v176, v32, v176
	v_mul_f32_e32 v177, v33, v177
	v_mul_f32_e32 v178, v34, v178
	v_mul_f32_e32 v179, v35, v179
	v_mul_f32_e32 v40, v44, v172
	v_mul_f32_e32 v41, v45, v173
	v_mul_f32_e32 v42, v46, v174
	v_mul_f32_e32 v43, v47, v175
	v_mul_f32_e32 v32, v36, v176
	v_mul_f32_e32 v33, v37, v177
	v_mul_f32_e32 v34, v38, v178
	v_mul_f32_e32 v35, v39, v179
	v_cvt_pk_bf16_f32 v180, v40, v41
	v_cvt_pk_bf16_f32 v181, v42, v43
	v_cvt_pk_bf16_f32 v182, v32, v33
	v_cvt_pk_bf16_f32 v183, v34, v35
	v_mov_b32_dpp v184, v180 quad_perm:[1,0,3,2] row_mask:0xf bank_mask:0xf bound_ctrl:1
	v_mov_b32_dpp v185, v181 quad_perm:[1,0,3,2] row_mask:0xf bank_mask:0xf bound_ctrl:1
	v_mov_b32_dpp v186, v182 quad_perm:[1,0,3,2] row_mask:0xf bank_mask:0xf bound_ctrl:1
	v_mov_b32_dpp v187, v183 quad_perm:[1,0,3,2] row_mask:0xf bank_mask:0xf bound_ctrl:1
	v_perm_b32 v180, v184, v180, v164
	v_perm_b32 v181, v185, v181, v164
	v_perm_b32 v182, v186, v182, v164
	v_perm_b32 v183, v187, v183, v164
	global_store_dword v169, v180, s[34:35]
	global_store_dword v170, v181, s[34:35]
	global_store_dword v169, v182, s[34:35] offset:32
	global_store_dword v170, v183, s[34:35] offset:32
	v_add_u32_e32 v169, 0xdc000, v166
	v_add_u32_e32 v170, 0xdec00, v166
	v_mul_f32_e32 v24, v24, v154
	v_mul_f32_e32 v25, v25, v155
	v_mul_f32_e32 v26, v26, v156
	v_mul_f32_e32 v27, v27, v157
	v_mul_f32_e32 v16, v16, v154
	v_mul_f32_e32 v17, v17, v155
	v_mul_f32_e32 v18, v18, v156
	v_mul_f32_e32 v19, v19, v157
	v_mul_f32_e32 v28, v28, v154
	v_mul_f32_e32 v29, v29, v155
	v_mul_f32_e32 v30, v30, v156
	v_mul_f32_e32 v31, v31, v157
	v_mul_f32_e32 v20, v20, v154
	v_mul_f32_e32 v21, v21, v155
	v_mul_f32_e32 v22, v22, v156
	v_mul_f32_e32 v23, v23, v157
	v_mul_f32_e32 v172, 0xbfb8aa3b, v24
	v_mul_f32_e32 v173, 0xbfb8aa3b, v25
	v_mul_f32_e32 v174, 0xbfb8aa3b, v26
	v_mul_f32_e32 v175, 0xbfb8aa3b, v27
	v_mul_f32_e32 v176, 0xbfb8aa3b, v16
	v_mul_f32_e32 v177, 0xbfb8aa3b, v17
	v_mul_f32_e32 v178, 0xbfb8aa3b, v18
	v_mul_f32_e32 v179, 0xbfb8aa3b, v19
	v_exp_f32_e32 v172, v172
	v_exp_f32_e32 v173, v173
	v_exp_f32_e32 v174, v174
	v_exp_f32_e32 v175, v175
	v_exp_f32_e32 v176, v176
	v_exp_f32_e32 v177, v177
	v_exp_f32_e32 v178, v178
	v_exp_f32_e32 v179, v179
	v_add_f32_e32 v172, 1.0, v172
	v_add_f32_e32 v173, 1.0, v173
	v_add_f32_e32 v174, 1.0, v174
	v_add_f32_e32 v175, 1.0, v175
	v_add_f32_e32 v176, 1.0, v176
; __device__ __forceinline__ float fast_silu(float z) { return z * __builtin_amdgcn_rcpf(1.f + __expf(-z)); }
; #define WAIT_L(n) asm volatile("s_waitcnt lgkmcnt(" #n ")" ::: "memory")
; #define BAR __builtin_amdgcn_s_barrier()
; template <class Epi>
; __device__ __forceinline__ void gemm_tile(const u16* __restrict__ A, const u16* __restrict__ Bt, int K,
;                                           int brow, int bcol, bool first, bool has_next, int nbrow, int nbcol, Epi epi) {
;     ...
;   WAIT_L(0); BAR;
;   __device__ __forceinline__ void operator()(f32x4 (&acc)[2][2][4][2], int brow, int bcol, int wr, int wc, int fr, int fq) const {
;     ...
; #pragma unroll
;         for (int n = 0; n < 2; ++n) {
;           float a[4];
; #pragma unroll
;           for (int j = 0; j < 4; ++j) {
;             float g = acc[ai][0][m][n][j] * rs[j], u = acc[ai][1][m][n][j] * rs[j];
;             a[j] = fast_silu(g) * u;
;           }
;           store_rm4(act, 2816, row0, t * 128 + wc * 32 + n * 16 + fr, a[0], a[1], a[2], a[3], fr & 1);
;         }
	v_add_f32_e32 v177, 1.0, v177
	v_add_f32_e32 v178, 1.0, v178
	v_add_f32_e32 v179, 1.0, v179
	v_rcp_f32_e32 v172, v172
	v_rcp_f32_e32 v173, v173
	v_rcp_f32_e32 v174, v174
	v_rcp_f32_e32 v175, v175
	v_rcp_f32_e32 v176, v176
	v_rcp_f32_e32 v177, v177
	v_rcp_f32_e32 v178, v178
	v_rcp_f32_e32 v179, v179
	v_mul_f32_e32 v172, v24, v172
	v_mul_f32_e32 v173, v25, v173
	v_mul_f32_e32 v174, v26, v174
	v_mul_f32_e32 v175, v27, v175
	v_mul_f32_e32 v176, v16, v176
	v_mul_f32_e32 v177, v17, v177
	v_mul_f32_e32 v178, v18, v178
	v_mul_f32_e32 v179, v19, v179
	v_mul_f32_e32 v24, v28, v172
	v_mul_f32_e32 v25, v29, v173
	v_mul_f32_e32 v26, v30, v174
	v_mul_f32_e32 v27, v31, v175
	v_mul_f32_e32 v16, v20, v176
	v_mul_f32_e32 v17, v21, v177
	v_mul_f32_e32 v18, v22, v178
	v_mul_f32_e32 v19, v23, v179
	v_cvt_pk_bf16_f32 v180, v24, v25
	v_cvt_pk_bf16_f32 v181, v26, v27
	v_cvt_pk_bf16_f32 v182, v16, v17
	v_cvt_pk_bf16_f32 v183, v18, v19
	v_mov_b32_dpp v184, v180 quad_perm:[1,0,3,2] row_mask:0xf bank_mask:0xf bound_ctrl:1
	v_mov_b32_dpp v185, v181 quad_perm:[1,0,3,2] row_mask:0xf bank_mask:0xf bound_ctrl:1
	v_mov_b32_dpp v186, v182 quad_perm:[1,0,3,2] row_mask:0xf bank_mask:0xf bound_ctrl:1
	v_mov_b32_dpp v187, v183 quad_perm:[1,0,3,2] row_mask:0xf bank_mask:0xf bound_ctrl:1
	v_perm_b32 v180, v184, v180, v164
	v_perm_b32 v181, v185, v181, v164
	v_perm_b32 v182, v186, v182, v164
	v_perm_b32 v183, v187, v183, v164
	global_store_dword v169, v180, s[34:35]
	global_store_dword v170, v181, s[34:35]
	global_store_dword v169, v182, s[34:35] offset:32
	global_store_dword v170, v183, s[34:35] offset:32
	v_add_u32_e32 v169, 0xf2000, v166
	v_add_u32_e32 v170, 0xf4c00, v166
	v_mul_f32_e32 v8, v8, v158
	v_mul_f32_e32 v9, v9, v159
	v_mul_f32_e32 v10, v10, v160
	v_mul_f32_e32 v11, v11, v161
	v_mul_f32_e32 v0, v0, v158
	v_mul_f32_e32 v1, v1, v159
	v_mul_f32_e32 v2, v2, v160
	v_mul_f32_e32 v3, v3, v161
	v_mul_f32_e32 v12, v12, v158
	v_mul_f32_e32 v13, v13, v159
	v_mul_f32_e32 v14, v14, v160
	v_mul_f32_e32 v15, v15, v161
	v_mul_f32_e32 v4, v4, v158
	v_mul_f32_e32 v5, v5, v159
	v_mul_f32_e32 v6, v6, v160
	v_mul_f32_e32 v7, v7, v161
	v_mul_f32_e32 v172, 0xbfb8aa3b, v8
	v_mul_f32_e32 v173, 0xbfb8aa3b, v9
	v_mul_f32_e32 v174, 0xbfb8aa3b, v10
	v_mul_f32_e32 v175, 0xbfb8aa3b, v11
	v_mul_f32_e32 v176, 0xbfb8aa3b, v0
	v_mul_f32_e32 v177, 0xbfb8aa3b, v1
	v_mul_f32_e32 v178, 0xbfb8aa3b, v2
	v_mul_f32_e32 v179, 0xbfb8aa3b, v3
	v_exp_f32_e32 v172, v172
	v_exp_f32_e32 v173, v173
	v_exp_f32_e32 v174, v174
	v_exp_f32_e32 v175, v175
	v_exp_f32_e32 v176, v176
	v_exp_f32_e32 v177, v177
	v_exp_f32_e32 v178, v178
	v_exp_f32_e32 v179, v179
	v_add_f32_e32 v172, 1.0, v172
	v_add_f32_e32 v173, 1.0, v173
	v_add_f32_e32 v174, 1.0, v174
	v_add_f32_e32 v175, 1.0, v175
	v_add_f32_e32 v176, 1.0, v176
	v_add_f32_e32 v177, 1.0, v177
	v_add_f32_e32 v178, 1.0, v178
	v_add_f32_e32 v179, 1.0, v179
	v_rcp_f32_e32 v172, v172
	v_rcp_f32_e32 v173, v173
	v_rcp_f32_e32 v174, v174
	v_rcp_f32_e32 v175, v175
	v_rcp_f32_e32 v176, v176
	v_rcp_f32_e32 v177, v177
	v_rcp_f32_e32 v178, v178
	v_rcp_f32_e32 v179, v179
	v_mul_f32_e32 v172, v8, v172
	v_mul_f32_e32 v173, v9, v173
	v_mul_f32_e32 v174, v10, v174
	v_mul_f32_e32 v175, v11, v175
	v_mul_f32_e32 v176, v0, v176
	v_mul_f32_e32 v177, v1, v177
	v_mul_f32_e32 v178, v2, v178
	v_mul_f32_e32 v179, v3, v179
	v_mul_f32_e32 v8, v12, v172
	v_mul_f32_e32 v9, v13, v173
	v_mul_f32_e32 v10, v14, v174
	v_mul_f32_e32 v11, v15, v175
	v_mul_f32_e32 v0, v4, v176
	v_mul_f32_e32 v1, v5, v177
	v_mul_f32_e32 v2, v6, v178
	v_mul_f32_e32 v3, v7, v179
	v_cvt_pk_bf16_f32 v180, v8, v9
	v_cvt_pk_bf16_f32 v181, v10, v11
	v_cvt_pk_bf16_f32 v182, v0, v1
	v_cvt_pk_bf16_f32 v183, v2, v3
	v_mov_b32_dpp v184, v180 quad_perm:[1,0,3,2] row_mask:0xf bank_mask:0xf bound_ctrl:1
	v_mov_b32_dpp v185, v181 quad_perm:[1,0,3,2] row_mask:0xf bank_mask:0xf bound_ctrl:1
	v_mov_b32_dpp v186, v182 quad_perm:[1,0,3,2] row_mask:0xf bank_mask:0xf bound_ctrl:1
	v_mov_b32_dpp v187, v183 quad_perm:[1,0,3,2] row_mask:0xf bank_mask:0xf bound_ctrl:1
	v_perm_b32 v180, v184, v180, v164
	v_perm_b32 v181, v185, v181, v164
	v_perm_b32 v182, v186, v182, v164
	v_perm_b32 v183, v187, v183, v164
	global_store_dword v169, v180, s[34:35]
	global_store_dword v170, v181, s[34:35]
	global_store_dword v169, v182, s[34:35] offset:32
	global_store_dword v170, v183, s[34:35] offset:32
	s_waitcnt lgkmcnt(0)
	s_cmp_lg_u32 s64, 22
	s_mov_b32 s2, s30
	s_mov_b32 s0, s28
	s_mov_b32 s1, s64
	s_barrier
	s_cbranch_scc0 .LBB0_597

; __global__ void __launch_bounds__(512) fwd_mega(P pin) {
;   cg::grid_group grid = cg::this_grid();
;   P p = pin; p.wv = __builtin_amdgcn_readfirstlane((int)(threadIdx.x >> 6));
	.amdhsa_kernel _Z8fwd_mega1P
		.amdhsa_group_segment_fixed_size 1040
		.amdhsa_private_segment_fixed_size 0
		.amdhsa_kernarg_size 408
		.amdhsa_user_sgpr_count 2
		.amdhsa_user_sgpr_dispatch_ptr 0
		.amdhsa_user_sgpr_queue_ptr 0
		.amdhsa_user_sgpr_kernarg_segment_ptr 1
		.amdhsa_user_sgpr_dispatch_id 0
		.amdhsa_user_sgpr_kernarg_preload_length 0
		.amdhsa_user_sgpr_kernarg_preload_offset 0
		.amdhsa_user_sgpr_private_segment_size 0
		.amdhsa_uses_dynamic_stack 0
		.amdhsa_enable_private_segment 0
		.amdhsa_system_sgpr_workgroup_id_x 1
		.amdhsa_system_sgpr_workgroup_id_y 0
		.amdhsa_system_sgpr_workgroup_id_z 0
		.amdhsa_system_sgpr_workgroup_info 0
		.amdhsa_system_vgpr_workitem_id 2
		.amdhsa_next_free_vgpr 256
		.amdhsa_next_free_sgpr 102
		.amdhsa_accum_offset 256
		.amdhsa_reserve_vcc 1
		.amdhsa_float_round_mode_32 0
		.amdhsa_float_round_mode_16_64 0
		.amdhsa_float_denorm_mode_32 3
		.amdhsa_float_denorm_mode_16_64 3
		.amdhsa_dx10_clamp 1
		.amdhsa_ieee_mode 1
		.amdhsa_fp16_overflow 0
		.amdhsa_tg_split 0
		.amdhsa_exception_fp_ieee_invalid_op 0
		.amdhsa_exception_fp_denorm_src 0
		.amdhsa_exception_fp_ieee_div_zero 0
		.amdhsa_exception_fp_ieee_overflow 0
		.amdhsa_exception_fp_ieee_underflow 0
		.amdhsa_exception_fp_ieee_inexact 0
		.amdhsa_exception_int_div_zero 0
	.end_amdhsa_kernel

; __global__ void __launch_bounds__(512) fwd_mega(P pin) {
;   cg::grid_group grid = cg::this_grid();
;   P p = pin; p.wv = __builtin_amdgcn_readfirstlane((int)(threadIdx.x >> 6));
amdhsa.kernels:
  - .agpr_count:     0
    .args:
      - .offset:         0
        .size:           152
        .value_kind:     by_value
      - .offset:         152
        .size:           4
        .value_kind:     hidden_block_count_x
      - .offset:         156
        .size:           4
        .value_kind:     hidden_block_count_y
      - .offset:         160
        .size:           4
        .value_kind:     hidden_block_count_z
      - .offset:         164
        .size:           2
        .value_kind:     hidden_group_size_x
      - .offset:         166
        .size:           2
        .value_kind:     hidden_group_size_y
      - .offset:         168
        .size:           2
        .value_kind:     hidden_group_size_z
      - .offset:         170
        .size:           2
        .value_kind:     hidden_remainder_x
      - .offset:         172
        .size:           2
        .value_kind:     hidden_remainder_y
      - .offset:         174
        .size:           2
        .value_kind:     hidden_remainder_z
      - .offset:         192
        .size:           8
        .value_kind:     hidden_global_offset_x
      - .offset:         200
        .size:           8
        .value_kind:     hidden_global_offset_y
      - .offset:         208
        .size:           8
        .value_kind:     hidden_global_offset_z
      - .offset:         216
        .size:           2
        .value_kind:     hidden_grid_dims
      - .offset:         240
        .size:           8
        .value_kind:     hidden_multigrid_sync_arg
      - .offset:         272
        .size:           4
        .value_kind:     hidden_dynamic_lds_size
    .group_segment_fixed_size: 1040
    .kernarg_segment_align: 8
    .kernarg_segment_size: 408
    .language:       OpenCL C
    .language_version:
      - 2
      - 0
    .max_flat_workgroup_size: 512
    .name:           _Z8fwd_mega1P
    .private_segment_fixed_size: 0
    .sgpr_count:     108
    .sgpr_spill_count: 3
    .symbol:         _Z8fwd_mega1P.kd
    .uniform_work_group_size: 1
    .uses_dynamic_stack: false
    .vgpr_count:     256
    .vgpr_spill_count: 0
    .wavefront_size: 64
